# speedup vs baseline: 1.0012x; 1.0012x over previous
; template <int TN, bool NTS = false>
; __device__ __forceinline__ void store_tile_bf16(const f32x4 (&acc)[4][TN], bf16_t* __restrict__ dst, int ldd, bf16_t* sT,
;                                                 const int tidx) {
;     ...
; #pragma unroll
;   for (int c = tidx; c < 256 * CPR; c += NT) {
;     int row = c / CPR, cc = c % CPR;
;     const u32x4 v_ = *(const u32x4*)(sT + row * TS + cc * 8);
;     if (NTS) __builtin_nontemporal_store(v_, (u32x4*)(dst + (size_t)row * ldd + cc * 8));
;     else *(u32x4*)(dst + (size_t)row * ldd + cc * 8) = v_;
;   }
; __device__ __forceinline__ void phase_outproj(const Params& p, const int tidx) {
;     ...
;     store_tile_bf16<4>(acc, P + (size_t)mt * 256 * NP + OFF_OUT + nt * 128, NP, sA, tidx);
.LBB0_75:
	v_ashrrev_i32_e32 v11, 31, v10
	v_lshrrev_b32_e32 v11, 28, v11
	v_add_u32_e32 v14, 0x200, v10
	v_add_u32_e32 v11, v10, v11
	v_cmp_lt_i32_e64 s[12:13], s96, v10
	v_mov_b32_e32 v10, v14
	v_ashrrev_i32_e32 v14, 4, v11
	v_and_b32_e32 v11, -16, v11
	v_mov_b64_e32 v[12:13], s[14:15]
	v_add_u32_e32 v11, v8, v11
	s_or_b64 s[16:17], s[12:13], s[16:17]
	v_lshlrev_b32_e32 v18, 7, v14
	v_mad_i64_i32 v[16:17], s[12:13], v14, s3, v[12:13]
	ds_read_b128 v[12:15], v11
	v_sub_u32_e32 v18, v9, v18
	v_ashrrev_i32_e32 v19, 31, v18
	v_add_u32_e32 v8, 0x2000, v8
	v_add_u32_e32 v9, 0x1000, v9
	v_lshl_add_u64 v[16:17], v[18:19], 1, v[16:17]
	s_waitcnt lgkmcnt(0)
	global_store_dwordx4 v[16:17], v[12:15], off nt
	s_andn2_b64 exec, exec, s[16:17]
	s_cbranch_execnz .LBB0_75
	s_or_b64 exec, exec, s[16:17]
	s_branch .LBB0_40

; template <int TN, bool NTS = false>
; __device__ __forceinline__ void store_tile_bf16(const f32x4 (&acc)[4][TN], bf16_t* __restrict__ dst, int ldd, bf16_t* sT,
;                                                 const int tidx) {
;     ...
; #pragma unroll
;   for (int c = tidx; c < 256 * CPR; c += NT) {
;     int row = c / CPR, cc = c % CPR;
;     const u32x4 v_ = *(const u32x4*)(sT + row * TS + cc * 8);
;     if (NTS) __builtin_nontemporal_store(v_, (u32x4*)(dst + (size_t)row * ldd + cc * 8));
;     else *(u32x4*)(dst + (size_t)row * ldd + cc * 8) = v_;
;   }
; __device__ __forceinline__ void phase_merge(const Params& p, const int tidx) {
;     ...
;     store_tile_bf16<2>(mg, P + (size_t)mt * 256 * NP + OFF_MERGED + nt * 64, NP, sA, tidx);
.LBB0_87:
	v_ashrrev_i32_e32 v11, 31, v10
	v_lshrrev_b32_e32 v11, 29, v11
	v_add_u32_e32 v11, v10, v11
	v_add_u32_e32 v14, 0x200, v10
	s_movk_i32 s0, 0x5ff
	v_ashrrev_i32_e32 v11, 3, v11
	v_mov_b64_e32 v[12:13], s[12:13]
	v_cmp_lt_i32_e64 s[10:11], s0, v10
	v_mov_b32_e32 v10, v14
	v_lshl_add_u32 v14, v11, 4, v8
	s_or_b64 s[14:15], s[10:11], s[14:15]
	v_mad_i64_i32 v[16:17], s[10:11], v11, s3, v[12:13]
	ds_read_b128 v[12:15], v14
	v_lshlrev_b32_e32 v18, 6, v11
	v_sub_u32_e32 v18, v9, v18
	v_ashrrev_i32_e32 v19, 31, v18
	v_add_u32_e32 v8, 0x2000, v8
	v_add_u32_e32 v9, 0x1000, v9
	v_lshl_add_u64 v[16:17], v[18:19], 1, v[16:17]
	s_waitcnt lgkmcnt(0)
	global_store_dwordx4 v[16:17], v[12:15], off nt
	s_andn2_b64 exec, exec, s[14:15]
	s_cbranch_execnz .LBB0_87
	s_branch .LBB0_84

; template <int TN, bool NTS = false>
; __device__ __forceinline__ void store_tile_bf16(const f32x4 (&acc)[4][TN], bf16_t* __restrict__ dst, int ldd, bf16_t* sT,
;                                                 const int tidx) {
;     ...
; #pragma unroll
;   for (int c = tidx; c < 256 * CPR; c += NT) {
;     int row = c / CPR, cc = c % CPR;
;     const u32x4 v_ = *(const u32x4*)(sT + row * TS + cc * 8);
;     if (NTS) __builtin_nontemporal_store(v_, (u32x4*)(dst + (size_t)row * ldd + cc * 8));
;     else *(u32x4*)(dst + (size_t)row * ldd + cc * 8) = v_;
;   }
; __device__ __forceinline__ void phase_mlstm_qkv(const Params& p, const int tidx) {
;     ...
;     store_tile_bf16<4>(acc, O + (size_t)mt * 256 * 512 + h * 128, 512, sA, tidx);
.LBB0_391:
	v_ashrrev_i32_e32 v34, 31, v33
	v_lshrrev_b32_e32 v34, 28, v34
	v_add_u32_e32 v34, v33, v34
	v_add_u32_e32 v35, 0x200, v33
	v_ashrrev_i32_e32 v38, 4, v34
	v_and_b32_e32 v34, -16, v34
	v_cmp_lt_i32_e64 s[10:11], s96, v33
	v_mov_b32_e32 v33, v35
	v_lshlrev_b32_e32 v35, 7, v38
	v_add_u32_e32 v34, v31, v34
	v_sub_u32_e32 v40, v32, v35
	ds_read_b128 v[34:37], v34
	v_ashrrev_i32_e32 v39, 31, v38
	v_lshlrev_b64 v[38:39], 10, v[38:39]
	v_ashrrev_i32_e32 v41, 31, v40
	v_lshl_add_u64 v[38:39], s[12:13], 0, v[38:39]
	s_or_b64 s[14:15], s[10:11], s[14:15]
	v_add_u32_e32 v31, 0x2000, v31
	v_add_u32_e32 v32, 0x1000, v32
	v_lshl_add_u64 v[38:39], v[40:41], 1, v[38:39]
	s_waitcnt lgkmcnt(0)
	global_store_dwordx4 v[38:39], v[34:37], off nt
	s_andn2_b64 exec, exec, s[14:15]
	s_cbranch_execnz .LBB0_391
	s_branch .LBB0_388
